# EpiMid (P4 out-proj epilogue): bf16 residual x1 stores moved from part 1 into part 2 (from the y values still in the accumulators, 16-byte pieces via permlane16 swap); part 1 read-only with x loads pi
# speedup vs baseline: 1.0170x; 1.0107x over previous
; DI unsigned pk2(float lo, float hi) { unsigned r; asm("v_cvt_pk_bf16_f32 %0, %1, %2" : "=v"(r) : "v"(lo), "v"(hi)); return r; }
;     DI void operator()(f32x4 (&acc)[2][2][4][2], const pg8::Unit& u, int wr, int wc, int fr, int fq) const {
;     ...
; #pragma unroll
;         for (int ai = 0; ai < 2; ++ai)
; #pragma unroll
;             for (int m = 0; m < 4; ++m) { const int row = row0 + ai * 128 + m * 16; const float* gate = mod0 + (size_t)(row >> 12) * 3072 + 2048; float ss = 0.f;
; #pragma unroll
;                 for (int bj = 0; bj < 2; ++bj)
; #pragma unroll
;                     for (int n = 0; n < 2; ++n) { const int col = col0 + bj * 128 + n * 16; const size_t off = (size_t)row * DM + col;
;                         const f32x4 x = __builtin_nontemporal_load((const f32x4*)(xin + off)), gt = *(const f32x4*)(gate + col), y = x + gt * acc[ai][bj][m][n];
;                         acc[ai][bj][m][n] = y; ss += (y.x * y.x + y.y * y.y) + (y.z * y.z + y.w * y.w);
;                         u32x2 w; w.x = pk2(y.x, y.y); w.y = pk2(y.z, y.w); *(u32x2*)(xb + off) = w; }
;                 ss += __shfl_xor(ss, 16); ss += __shfl_xor(ss, 32);
;                 if (fq == 0) X[(ai * 128 + wr * 64 + m * 16 + fr) * 4 + wc] = ss;
;                 asm volatile("" ::: "memory"); }
.LBB0_776:
	s_lshl_b32 s10, s62, 8
	s_add_i32 s10, s10, s85
	v_or_b32_e32 v168, s10, v129
	s_ashr_i32 s10, s10, 12
	s_mulk_i32 s10, 0xc00
	s_ashr_i32 s11, s10, 31
	s_lshl_b64 s[10:11], s[10:11], 2
	s_add_u32 s10, s26, s10
	v_lshl_or_b32 v158, s64, 8, v179
	s_addc_u32 s11, s27, s11
	v_ashrrev_i32_e32 v169, 31, v168
	s_add_u32 s10, s10, 0x2000
	v_lshlrev_b64 v[202:203], 10, v[168:169]
	v_ashrrev_i32_e32 v159, 31, v158
	s_addc_u32 s11, s11, 0
	v_lshl_add_u64 v[162:163], v[202:203], 0, v[158:159]
	v_mov_b32_e32 v166, v226
	v_lshl_add_u64 v[204:205], v[162:163], 2, s[68:69]
	v_lshl_add_u64 v[170:171], v[158:159], 2, s[10:11]
	v_mov_b64_e32 v[160:161], v[204:205]
	s_mov_b32 s73, 0
	global_load_dwordx4 v[194:197], v[170:171], off offset:0
	global_load_dwordx4 v[198:201], v[170:171], off offset:64
	global_load_dwordx4 v[202:205], v[170:171], off offset:512
	global_load_dwordx4 v[206:209], v[170:171], off offset:576
	global_load_dwordx4 v[212:215], v[160:161], off offset:0 nt
	global_load_dwordx4 v[216:219], v[160:161], off offset:64 nt
	global_load_dwordx4 v[220:223], v[160:161], off offset:512 nt
	global_load_dwordx4 v[228:231], v[160:161], off offset:576 nt
	s_mov_b32 s72, 0x10000
	v_lshl_add_u64 v[170:171], v[160:161], 0, s[72:73]
	global_load_dwordx4 v[232:235], v[170:171], off offset:0 nt
	global_load_dwordx4 v[236:239], v[170:171], off offset:64 nt
	global_load_dwordx4 v[240:243], v[170:171], off offset:512 nt
	global_load_dwordx4 v[244:247], v[170:171], off offset:576 nt
	v_and_b32_e32 v173, 64, v191
	v_xor_b32_e32 v172, 16, v191
	v_add_u32_e32 v173, 64, v173
	v_xor_b32_e32 v250, 32, v191
	v_cmp_lt_i32_e32 vcc, v172, v173
	s_nop 1
	v_cndmask_b32_e32 v210, v191, v172, vcc
	v_cmp_lt_i32_e32 vcc, v250, v173
	v_lshlrev_b32_e32 v210, 2, v210
	s_nop 0
	v_cndmask_b32_e32 v193, v191, v250, vcc
	v_lshlrev_b32_e32 v193, 2, v193
	s_waitcnt vmcnt(4)
	v_pk_fma_f32 v[164:165], v[124:125], v[194:195], v[212:213]
	v_pk_fma_f32 v[162:163], v[126:127], v[196:197], v[214:215]
	v_mul_f32_e32 v173, v165, v165
	v_mul_f32_e32 v250, v163, v163
	v_fmac_f32_e32 v173, v164, v164
	v_fmac_f32_e32 v250, v162, v162
	v_add_f32_e32 v172, v173, v250
	v_pk_fma_f32 v[126:127], v[120:121], v[198:199], v[216:217]
	v_pk_fma_f32 v[122:123], v[122:123], v[200:201], v[218:219]
	v_mul_f32_e32 v173, v127, v127
	v_mul_f32_e32 v250, v123, v123
	v_fmac_f32_e32 v173, v126, v126
	v_fmac_f32_e32 v250, v122, v122
	v_add_f32_e32 v173, v173, v250
	v_add_f32_e32 v172, v172, v173
	v_pk_fma_f32 v[116:117], v[116:117], v[202:203], v[220:221]
	v_pk_fma_f32 v[118:119], v[118:119], v[204:205], v[222:223]
	v_mul_f32_e32 v173, v117, v117
	v_mul_f32_e32 v250, v119, v119
	v_fmac_f32_e32 v173, v116, v116
	v_fmac_f32_e32 v250, v118, v118
	v_add_f32_e32 v173, v173, v250
	v_add_f32_e32 v172, v172, v173
	v_pk_fma_f32 v[112:113], v[112:113], v[206:207], v[228:229]
	v_pk_fma_f32 v[114:115], v[114:115], v[208:209], v[230:231]
	v_mul_f32_e32 v173, v113, v113
	v_mul_f32_e32 v250, v115, v115
	v_fmac_f32_e32 v173, v112, v112
	v_fmac_f32_e32 v250, v114, v114
	v_add_f32_e32 v173, v173, v250
	v_add_f32_e32 v172, v172, v173
	s_mov_b32 s72, 0x20000
	v_lshl_add_u64 v[170:171], v[160:161], 0, s[72:73]
	global_load_dwordx4 v[212:215], v[170:171], off offset:0 nt
	global_load_dwordx4 v[216:219], v[170:171], off offset:64 nt
	global_load_dwordx4 v[220:223], v[170:171], off offset:512 nt
	global_load_dwordx4 v[228:231], v[170:171], off offset:576 nt
	ds_bpermute_b32 v227, v210, v172
	s_waitcnt lgkmcnt(0)
	v_add_f32_e32 v172, v172, v227
	ds_bpermute_b32 v227, v193, v172
	s_waitcnt lgkmcnt(0)
	v_add_f32_e32 v172, v172, v227
	s_and_saveexec_b64 s[10:11], s[6:7]
	ds_write_b32 v180, v172
	s_or_b64 exec, exec, s[10:11]
	s_waitcnt vmcnt(4)
	v_pk_fma_f32 v[108:109], v[108:109], v[194:195], v[232:233]
	v_pk_fma_f32 v[110:111], v[110:111], v[196:197], v[234:235]
	v_mul_f32_e32 v173, v109, v109
	v_mul_f32_e32 v250, v111, v111
	v_fmac_f32_e32 v173, v108, v108
	v_fmac_f32_e32 v250, v110, v110
	v_add_f32_e32 v172, v173, v250
	v_pk_fma_f32 v[104:105], v[104:105], v[198:199], v[236:237]
	v_pk_fma_f32 v[106:107], v[106:107], v[200:201], v[238:239]
	v_mul_f32_e32 v173, v105, v105
	v_mul_f32_e32 v250, v107, v107
	v_fmac_f32_e32 v173, v104, v104
	v_fmac_f32_e32 v250, v106, v106
	v_add_f32_e32 v173, v173, v250
	v_add_f32_e32 v172, v172, v173
	v_pk_fma_f32 v[100:101], v[100:101], v[202:203], v[240:241]
	v_pk_fma_f32 v[102:103], v[102:103], v[204:205], v[242:243]
	v_mul_f32_e32 v173, v101, v101
	v_mul_f32_e32 v250, v103, v103
	v_fmac_f32_e32 v173, v100, v100
	v_fmac_f32_e32 v250, v102, v102
	v_add_f32_e32 v173, v173, v250
	v_add_f32_e32 v172, v172, v173
	v_pk_fma_f32 v[96:97], v[96:97], v[206:207], v[244:245]
	v_pk_fma_f32 v[98:99], v[98:99], v[208:209], v[246:247]
	v_mul_f32_e32 v173, v97, v97
	v_mul_f32_e32 v250, v99, v99
	v_fmac_f32_e32 v173, v96, v96
	v_fmac_f32_e32 v250, v98, v98
	v_add_f32_e32 v173, v173, v250
	v_add_f32_e32 v172, v172, v173
	s_mov_b32 s72, 0x30000
	v_lshl_add_u64 v[170:171], v[160:161], 0, s[72:73]
	global_load_dwordx4 v[232:235], v[170:171], off offset:0 nt
	global_load_dwordx4 v[236:239], v[170:171], off offset:64 nt
	global_load_dwordx4 v[240:243], v[170:171], off offset:512 nt
	global_load_dwordx4 v[244:247], v[170:171], off offset:576 nt
	ds_bpermute_b32 v227, v210, v172
	s_waitcnt lgkmcnt(0)
	v_add_f32_e32 v172, v172, v227
	ds_bpermute_b32 v227, v193, v172
	s_waitcnt lgkmcnt(0)
	v_add_f32_e32 v172, v172, v227
	s_and_saveexec_b64 s[10:11], s[6:7]
	ds_write_b32 v180, v172 offset:256
	s_or_b64 exec, exec, s[10:11]
	s_waitcnt vmcnt(4)
; DI unsigned pk2(float lo, float hi) { unsigned r; asm("v_cvt_pk_bf16_f32 %0, %1, %2" : "=v"(r) : "v"(lo), "v"(hi)); return r; }
;     DI void operator()(f32x4 (&acc)[2][2][4][2], const pg8::Unit& u, int wr, int wc, int fr, int fq) const {
;     ...
; #pragma unroll
;         for (int ai = 0; ai < 2; ++ai)
; #pragma unroll
;             for (int m = 0; m < 4; ++m) { const int row = row0 + ai * 128 + m * 16; const float* gate = mod0 + (size_t)(row >> 12) * 3072 + 2048; float ss = 0.f;
; #pragma unroll
;                 for (int bj = 0; bj < 2; ++bj)
; #pragma unroll
;                     for (int n = 0; n < 2; ++n) { const int col = col0 + bj * 128 + n * 16; const size_t off = (size_t)row * DM + col;
;                         const f32x4 x = __builtin_nontemporal_load((const f32x4*)(xin + off)), gt = *(const f32x4*)(gate + col), y = x + gt * acc[ai][bj][m][n];
;                         acc[ai][bj][m][n] = y; ss += (y.x * y.x + y.y * y.y) + (y.z * y.z + y.w * y.w);
;                         u32x2 w; w.x = pk2(y.x, y.y); w.y = pk2(y.z, y.w); *(u32x2*)(xb + off) = w; }
;                 ss += __shfl_xor(ss, 16); ss += __shfl_xor(ss, 32);
;                 if (fq == 0) X[(ai * 128 + wr * 64 + m * 16 + fr) * 4 + wc] = ss;
;                 asm volatile("" ::: "memory"); }
	v_pk_fma_f32 v[92:93], v[92:93], v[194:195], v[212:213]
	v_pk_fma_f32 v[94:95], v[94:95], v[196:197], v[214:215]
	v_mul_f32_e32 v173, v93, v93
	v_mul_f32_e32 v250, v95, v95
	v_fmac_f32_e32 v173, v92, v92
	v_fmac_f32_e32 v250, v94, v94
	v_add_f32_e32 v172, v173, v250
	v_pk_fma_f32 v[88:89], v[88:89], v[198:199], v[216:217]
	v_pk_fma_f32 v[90:91], v[90:91], v[200:201], v[218:219]
	v_mul_f32_e32 v173, v89, v89
	v_mul_f32_e32 v250, v91, v91
	v_fmac_f32_e32 v173, v88, v88
	v_fmac_f32_e32 v250, v90, v90
	v_add_f32_e32 v173, v173, v250
	v_add_f32_e32 v172, v172, v173
	v_pk_fma_f32 v[84:85], v[84:85], v[202:203], v[220:221]
	v_pk_fma_f32 v[86:87], v[86:87], v[204:205], v[222:223]
	v_mul_f32_e32 v173, v85, v85
	v_mul_f32_e32 v250, v87, v87
	v_fmac_f32_e32 v173, v84, v84
	v_fmac_f32_e32 v250, v86, v86
	v_add_f32_e32 v173, v173, v250
	v_add_f32_e32 v172, v172, v173
	v_pk_fma_f32 v[80:81], v[80:81], v[206:207], v[228:229]
	v_pk_fma_f32 v[82:83], v[82:83], v[208:209], v[230:231]
	v_mul_f32_e32 v173, v81, v81
	v_mul_f32_e32 v250, v83, v83
	v_fmac_f32_e32 v173, v80, v80
	v_fmac_f32_e32 v250, v82, v82
	v_add_f32_e32 v173, v173, v250
	v_add_f32_e32 v172, v172, v173
	s_mov_b32 s72, 0x80000
	v_lshl_add_u64 v[170:171], v[160:161], 0, s[72:73]
	global_load_dwordx4 v[212:215], v[170:171], off offset:0 nt
	global_load_dwordx4 v[216:219], v[170:171], off offset:64 nt
	global_load_dwordx4 v[220:223], v[170:171], off offset:512 nt
	global_load_dwordx4 v[228:231], v[170:171], off offset:576 nt
	ds_bpermute_b32 v227, v210, v172
	s_waitcnt lgkmcnt(0)
	v_add_f32_e32 v172, v172, v227
	ds_bpermute_b32 v227, v193, v172
	s_waitcnt lgkmcnt(0)
	v_add_f32_e32 v172, v172, v227
	s_and_saveexec_b64 s[10:11], s[6:7]
	ds_write_b32 v180, v172 offset:512
	s_or_b64 exec, exec, s[10:11]
	s_waitcnt vmcnt(4)
	v_pk_fma_f32 v[76:77], v[76:77], v[194:195], v[232:233]
	v_pk_fma_f32 v[78:79], v[78:79], v[196:197], v[234:235]
	v_mul_f32_e32 v173, v77, v77
	v_mul_f32_e32 v250, v79, v79
	v_fmac_f32_e32 v173, v76, v76
	v_fmac_f32_e32 v250, v78, v78
	v_add_f32_e32 v172, v173, v250
	v_pk_fma_f32 v[72:73], v[72:73], v[198:199], v[236:237]
	v_pk_fma_f32 v[74:75], v[74:75], v[200:201], v[238:239]
	v_mul_f32_e32 v173, v73, v73
	v_mul_f32_e32 v250, v75, v75
	v_fmac_f32_e32 v173, v72, v72
	v_fmac_f32_e32 v250, v74, v74
	v_add_f32_e32 v173, v173, v250
	v_add_f32_e32 v172, v172, v173
	v_pk_fma_f32 v[68:69], v[68:69], v[202:203], v[240:241]
	v_pk_fma_f32 v[70:71], v[70:71], v[204:205], v[242:243]
	v_mul_f32_e32 v173, v69, v69
	v_mul_f32_e32 v250, v71, v71
	v_fmac_f32_e32 v173, v68, v68
	v_fmac_f32_e32 v250, v70, v70
	v_add_f32_e32 v173, v173, v250
	v_add_f32_e32 v172, v172, v173
	v_pk_fma_f32 v[64:65], v[64:65], v[206:207], v[244:245]
	v_pk_fma_f32 v[66:67], v[66:67], v[208:209], v[246:247]
	v_mul_f32_e32 v173, v65, v65
	v_mul_f32_e32 v250, v67, v67
	v_fmac_f32_e32 v173, v64, v64
	v_fmac_f32_e32 v250, v66, v66
	v_add_f32_e32 v173, v173, v250
	v_add_f32_e32 v172, v172, v173
	s_mov_b32 s72, 0x90000
	v_lshl_add_u64 v[170:171], v[160:161], 0, s[72:73]
	global_load_dwordx4 v[232:235], v[170:171], off offset:0 nt
	global_load_dwordx4 v[236:239], v[170:171], off offset:64 nt
	global_load_dwordx4 v[240:243], v[170:171], off offset:512 nt
	global_load_dwordx4 v[244:247], v[170:171], off offset:576 nt
	ds_bpermute_b32 v227, v210, v172
	s_waitcnt lgkmcnt(0)
	v_add_f32_e32 v172, v172, v227
	ds_bpermute_b32 v227, v193, v172
	s_waitcnt lgkmcnt(0)
	v_add_f32_e32 v172, v172, v227
	s_and_saveexec_b64 s[10:11], s[6:7]
	ds_write_b32 v180, v172 offset:768
	s_or_b64 exec, exec, s[10:11]
	s_waitcnt vmcnt(4)
	v_pk_fma_f32 v[60:61], v[60:61], v[194:195], v[212:213]
	v_pk_fma_f32 v[62:63], v[62:63], v[196:197], v[214:215]
	v_mul_f32_e32 v173, v61, v61
	v_mul_f32_e32 v250, v63, v63
	v_fmac_f32_e32 v173, v60, v60
	v_fmac_f32_e32 v250, v62, v62
	v_add_f32_e32 v172, v173, v250
	v_pk_fma_f32 v[56:57], v[56:57], v[198:199], v[216:217]
	v_pk_fma_f32 v[58:59], v[58:59], v[200:201], v[218:219]
	v_mul_f32_e32 v173, v57, v57
	v_mul_f32_e32 v250, v59, v59
	v_fmac_f32_e32 v173, v56, v56
	v_fmac_f32_e32 v250, v58, v58
	v_add_f32_e32 v173, v173, v250
	v_add_f32_e32 v172, v172, v173
	v_pk_fma_f32 v[52:53], v[52:53], v[202:203], v[220:221]
	v_pk_fma_f32 v[54:55], v[54:55], v[204:205], v[222:223]
	v_mul_f32_e32 v173, v53, v53
	v_mul_f32_e32 v250, v55, v55
	v_fmac_f32_e32 v173, v52, v52
	v_fmac_f32_e32 v250, v54, v54
	v_add_f32_e32 v173, v173, v250
	v_add_f32_e32 v172, v172, v173
	v_pk_fma_f32 v[48:49], v[48:49], v[206:207], v[228:229]
	v_pk_fma_f32 v[50:51], v[50:51], v[208:209], v[230:231]
	v_mul_f32_e32 v173, v49, v49
	v_mul_f32_e32 v250, v51, v51
	v_fmac_f32_e32 v173, v48, v48
	v_fmac_f32_e32 v250, v50, v50
	v_add_f32_e32 v173, v173, v250
	v_add_f32_e32 v172, v172, v173
	s_mov_b32 s72, 0xa0000
	v_lshl_add_u64 v[170:171], v[160:161], 0, s[72:73]
	global_load_dwordx4 v[212:215], v[170:171], off offset:0 nt
	global_load_dwordx4 v[216:219], v[170:171], off offset:64 nt
	global_load_dwordx4 v[220:223], v[170:171], off offset:512 nt
	global_load_dwordx4 v[228:231], v[170:171], off offset:576 nt
	ds_bpermute_b32 v227, v210, v172
	s_waitcnt lgkmcnt(0)
	v_add_f32_e32 v172, v172, v227
	ds_bpermute_b32 v227, v193, v172
	s_waitcnt lgkmcnt(0)
	v_add_f32_e32 v172, v172, v227
	s_and_saveexec_b64 s[10:11], s[6:7]
	ds_write_b32 v180, v172 offset:2048
	s_or_b64 exec, exec, s[10:11]
	s_waitcnt vmcnt(4)
; #define LAS __attribute__((address_space(3)))
; DI unsigned pk2(float lo, float hi) { unsigned r; asm("v_cvt_pk_bf16_f32 %0, %1, %2" : "=v"(r) : "v"(lo), "v"(hi)); return r; }
;     DI void operator()(f32x4 (&acc)[2][2][4][2], const pg8::Unit& u, int wr, int wc, int fr, int fq) const {
;     ...
; #pragma unroll
;         for (int ai = 0; ai < 2; ++ai)
; #pragma unroll
;             for (int m = 0; m < 4; ++m) { const int row = row0 + ai * 128 + m * 16; const float* gate = mod0 + (size_t)(row >> 12) * 3072 + 2048; float ss = 0.f;
; #pragma unroll
;                 for (int bj = 0; bj < 2; ++bj)
; #pragma unroll
;                     for (int n = 0; n < 2; ++n) { const int col = col0 + bj * 128 + n * 16; const size_t off = (size_t)row * DM + col;
;                         const f32x4 x = __builtin_nontemporal_load((const f32x4*)(xin + off)), gt = *(const f32x4*)(gate + col), y = x + gt * acc[ai][bj][m][n];
;                         acc[ai][bj][m][n] = y; ss += (y.x * y.x + y.y * y.y) + (y.z * y.z + y.w * y.w);
;                         u32x2 w; w.x = pk2(y.x, y.y); w.y = pk2(y.z, y.w); *(u32x2*)(xb + off) = w; }
;                 ss += __shfl_xor(ss, 16); ss += __shfl_xor(ss, 32);
;                 if (fq == 0) X[(ai * 128 + wr * 64 + m * 16 + fr) * 4 + wc] = ss;
;                 asm volatile("" ::: "memory"); }
;         asm volatile("s_waitcnt lgkmcnt(0)" ::: "memory"); __builtin_amdgcn_s_barrier(); asm volatile("" ::: "memory");
;         if (tid < 256) { const f32x4 pp = *(const LAS f32x4*)(X + tid * 4);
;             __hip_atomic_store(slots + ((size_t)u.pm * 256 + tid) * 4 + u.pn, (pp.x + pp.y) + (pp.z + pp.w), __ATOMIC_RELAXED, __HIP_MEMORY_SCOPE_AGENT); }
	v_pk_fma_f32 v[44:45], v[44:45], v[194:195], v[232:233]
	v_pk_fma_f32 v[46:47], v[46:47], v[196:197], v[234:235]
	v_mul_f32_e32 v173, v45, v45
	v_mul_f32_e32 v250, v47, v47
	v_fmac_f32_e32 v173, v44, v44
	v_fmac_f32_e32 v250, v46, v46
	v_add_f32_e32 v172, v173, v250
	v_pk_fma_f32 v[40:41], v[40:41], v[198:199], v[236:237]
	v_pk_fma_f32 v[42:43], v[42:43], v[200:201], v[238:239]
	v_mul_f32_e32 v173, v41, v41
	v_mul_f32_e32 v250, v43, v43
	v_fmac_f32_e32 v173, v40, v40
	v_fmac_f32_e32 v250, v42, v42
	v_add_f32_e32 v173, v173, v250
	v_add_f32_e32 v172, v172, v173
	v_pk_fma_f32 v[36:37], v[36:37], v[202:203], v[240:241]
	v_pk_fma_f32 v[38:39], v[38:39], v[204:205], v[242:243]
	v_mul_f32_e32 v173, v37, v37
	v_mul_f32_e32 v250, v39, v39
	v_fmac_f32_e32 v173, v36, v36
	v_fmac_f32_e32 v250, v38, v38
	v_add_f32_e32 v173, v173, v250
	v_add_f32_e32 v172, v172, v173
	v_pk_fma_f32 v[32:33], v[32:33], v[206:207], v[244:245]
	v_pk_fma_f32 v[34:35], v[34:35], v[208:209], v[246:247]
	v_mul_f32_e32 v173, v33, v33
	v_mul_f32_e32 v250, v35, v35
	v_fmac_f32_e32 v173, v32, v32
	v_fmac_f32_e32 v250, v34, v34
	v_add_f32_e32 v173, v173, v250
	v_add_f32_e32 v172, v172, v173
	s_mov_b32 s72, 0xb0000
	v_lshl_add_u64 v[170:171], v[160:161], 0, s[72:73]
	global_load_dwordx4 v[232:235], v[170:171], off offset:0 nt
	global_load_dwordx4 v[236:239], v[170:171], off offset:64 nt
	global_load_dwordx4 v[240:243], v[170:171], off offset:512 nt
	global_load_dwordx4 v[244:247], v[170:171], off offset:576 nt
	ds_bpermute_b32 v227, v210, v172
	s_waitcnt lgkmcnt(0)
	v_add_f32_e32 v172, v172, v227
	ds_bpermute_b32 v227, v193, v172
	s_waitcnt lgkmcnt(0)
	v_add_f32_e32 v172, v172, v227
	s_and_saveexec_b64 s[10:11], s[6:7]
	ds_write_b32 v180, v172 offset:2304
	s_or_b64 exec, exec, s[10:11]
	s_waitcnt vmcnt(4)
	v_pk_fma_f32 v[28:29], v[28:29], v[194:195], v[212:213]
	v_pk_fma_f32 v[30:31], v[30:31], v[196:197], v[214:215]
	v_mul_f32_e32 v173, v29, v29
	v_mul_f32_e32 v250, v31, v31
	v_fmac_f32_e32 v173, v28, v28
	v_fmac_f32_e32 v250, v30, v30
	v_add_f32_e32 v172, v173, v250
	v_pk_fma_f32 v[24:25], v[24:25], v[198:199], v[216:217]
	v_pk_fma_f32 v[26:27], v[26:27], v[200:201], v[218:219]
	v_mul_f32_e32 v173, v25, v25
	v_mul_f32_e32 v250, v27, v27
	v_fmac_f32_e32 v173, v24, v24
	v_fmac_f32_e32 v250, v26, v26
	v_add_f32_e32 v173, v173, v250
	v_add_f32_e32 v172, v172, v173
	v_pk_fma_f32 v[20:21], v[20:21], v[202:203], v[220:221]
	v_pk_fma_f32 v[22:23], v[22:23], v[204:205], v[222:223]
	v_mul_f32_e32 v173, v21, v21
	v_mul_f32_e32 v250, v23, v23
	v_fmac_f32_e32 v173, v20, v20
	v_fmac_f32_e32 v250, v22, v22
	v_add_f32_e32 v173, v173, v250
	v_add_f32_e32 v172, v172, v173
	v_pk_fma_f32 v[16:17], v[16:17], v[206:207], v[228:229]
	v_pk_fma_f32 v[18:19], v[18:19], v[208:209], v[230:231]
	v_mul_f32_e32 v173, v17, v17
	v_mul_f32_e32 v250, v19, v19
	v_fmac_f32_e32 v173, v16, v16
	v_fmac_f32_e32 v250, v18, v18
	v_add_f32_e32 v173, v173, v250
	v_add_f32_e32 v172, v172, v173
	ds_bpermute_b32 v227, v210, v172
	s_waitcnt lgkmcnt(0)
	v_add_f32_e32 v172, v172, v227
	ds_bpermute_b32 v227, v193, v172
	s_waitcnt lgkmcnt(0)
	v_add_f32_e32 v172, v172, v227
	s_and_saveexec_b64 s[10:11], s[6:7]
	ds_write_b32 v180, v172 offset:2560
	s_or_b64 exec, exec, s[10:11]
	s_waitcnt vmcnt(0)
	v_pk_fma_f32 v[12:13], v[12:13], v[194:195], v[232:233]
	v_pk_fma_f32 v[14:15], v[14:15], v[196:197], v[234:235]
	v_mul_f32_e32 v173, v13, v13
	v_mul_f32_e32 v250, v15, v15
	v_fmac_f32_e32 v173, v12, v12
	v_fmac_f32_e32 v250, v14, v14
	v_add_f32_e32 v172, v173, v250
	v_pk_fma_f32 v[8:9], v[8:9], v[198:199], v[236:237]
	v_pk_fma_f32 v[10:11], v[10:11], v[200:201], v[238:239]
	v_mul_f32_e32 v173, v9, v9
	v_mul_f32_e32 v250, v11, v11
	v_fmac_f32_e32 v173, v8, v8
	v_fmac_f32_e32 v250, v10, v10
	v_add_f32_e32 v173, v173, v250
	v_add_f32_e32 v172, v172, v173
	v_pk_fma_f32 v[4:5], v[4:5], v[202:203], v[240:241]
	v_pk_fma_f32 v[6:7], v[6:7], v[204:205], v[242:243]
	v_mul_f32_e32 v173, v5, v5
	v_mul_f32_e32 v250, v7, v7
	v_fmac_f32_e32 v173, v4, v4
	v_fmac_f32_e32 v250, v6, v6
	v_add_f32_e32 v173, v173, v250
	v_add_f32_e32 v172, v172, v173
	v_pk_fma_f32 v[0:1], v[0:1], v[206:207], v[244:245]
	v_pk_fma_f32 v[2:3], v[2:3], v[208:209], v[246:247]
	v_mul_f32_e32 v173, v1, v1
	v_mul_f32_e32 v250, v3, v3
	v_fmac_f32_e32 v173, v0, v0
	v_fmac_f32_e32 v250, v2, v2
	v_add_f32_e32 v173, v173, v250
	v_add_f32_e32 v172, v172, v173
	ds_bpermute_b32 v227, v210, v172
	s_waitcnt lgkmcnt(0)
	v_add_f32_e32 v172, v172, v227
	ds_bpermute_b32 v227, v193, v172
	s_waitcnt lgkmcnt(0)
	v_add_f32_e32 v172, v172, v227
	s_and_saveexec_b64 s[10:11], s[6:7]
	ds_write_b32 v180, v172 offset:2816
	s_or_b64 exec, exec, s[10:11]
	v_or_b32_e32 v160, 16, v158
	v_or_b32_e32 v124, 0x80, v158
	v_or_b32_e32 v120, 0x90, v158
	v_ashrrev_i32_e32 v161, 31, v160
	v_ashrrev_i32_e32 v125, 31, v124
	v_ashrrev_i32_e32 v121, 31, v120
	v_mov_b32_e32 v166, v226
	s_waitcnt lgkmcnt(0)
	s_barrier
	s_movk_i32 s10, 0x100
	v_cmp_gt_i32_e64 s[10:11], s10, v166
	v_ashrrev_i32_e32 v167, 31, v166
	s_and_saveexec_b64 s[66:67], s[10:11]
	s_cbranch_execz .LBB0_794
	s_waitcnt lgkmcnt(0)
	v_lshl_add_u32 v168, v166, 4, 0
	v_add_u32_e32 v168, 0x20400, v168
	ds_read_b128 v[168:171], v168
	s_ashr_i32 s63, s62, 31
	s_lshl_b64 s[72:73], s[62:63], 12
	s_add_u32 s72, s18, s72
	s_addc_u32 s73, s19, s73
	s_waitcnt lgkmcnt(0)
	v_mov_b32_e32 v174, v169
	v_mov_b32_e32 v175, v170
	v_mov_b32_e32 v169, v171
	v_lshl_add_u64 v[172:173], v[166:167], 4, s[72:73]
	s_ashr_i32 s65, s64, 31
	v_pk_add_f32 v[168:169], v[174:175], v[168:169]
	v_lshl_add_u64 v[172:173], s[64:65], 2, v[172:173]
	v_pk_add_f32 v[168:169], v[168:169], v[168:169] op_sel:[0,1] op_sel_hi:[1,0]
	global_store_dword v[172:173], v168, off sc1

; DI unsigned pk2(float lo, float hi) { unsigned r; asm("v_cvt_pk_bf16_f32 %0, %1, %2" : "=v"(r) : "v"(lo), "v"(hi)); return r; }
;     DI void operator()(f32x4 (&acc)[2][2][4][2], const pg8::Unit& u, int wr, int wc, int fr, int fq) const {
;     ...
;                         u32x2 w; w.x = pk2(y.x, y.y); w.y = pk2(y.z, y.w); *(u32x2*)(xb + off) = w; }
;     ...
; #pragma unroll
;         for (int ai = 0; ai < 2; ++ai)
; #pragma unroll
;             for (int m = 0; m < 4; ++m) { const int rl = ai * 128 + wr * 64 + m * 16 + fr; const float rs = X[1024 + rl]; const size_t row = (size_t)u.pm * 256 + rl;
;                 const float* md = mod1 + (row >> 12) * 3072;
; #pragma unroll
;                 for (int bj = 0; bj < 2; ++bj)
; #pragma unroll
;                     for (int n = 0; n < 2; ++n) { const int col = col0 + bj * 128 + n * 16;
;                         const f32x4 gv = *(const f32x4*)(gno + col), sh = *(const f32x4*)(md + col), sc = *(const f32x4*)(md + 1024 + col);
;                         const f32x4 hv = acc[ai][bj][m][n] * rs * gv * (sc + 1.0f) + sh;
;                         u32x2 w; w.x = pk2(hv.x, hv.y); w.y = pk2(hv.z, hv.w); *(u32x2*)(H + row * DM + col) = w; }
.LBB0_808:
	s_or_b64 exec, exec, s[62:63]
	v_lshlrev_b64 v[172:173], 8, v[168:169]
	v_lshl_add_u64 v[176:177], v[172:173], 0, v[134:135]
	v_alignbit_b32 v166, v177, v176, 12
	v_mov_b64_e32 v[174:175], s[12:13]
	v_mad_u64_u32 v[170:171], s[10:11], v166, s94, v[174:175]
	v_lshrrev_b32_e32 v166, 12, v177
	v_mad_u32_u24 v171, v166, s94, v171
	v_lshl_add_u64 v[206:207], v[170:171], 0, s[48:49]
	v_lshlrev_b64 v[168:169], 2, v[158:159]
	s_waitcnt vmcnt(0) lgkmcnt(0)
	s_barrier
	v_lshl_add_u64 v[166:167], s[36:37], 0, v[168:169]
	v_lshl_add_u64 v[198:199], v[206:207], 0, v[168:169]
	v_lshl_add_u64 v[208:209], v[170:171], 0, v[168:169]
	global_load_dwordx4 v[130:133], v[166:167], off
	global_load_dwordx4 v[228:231], v[198:199], off
	global_load_dwordx4 v[178:181], v[208:209], off
	global_load_dwordx4 v[134:137], v[166:167], off offset:64
	global_load_dwordx4 v[232:235], v[198:199], off offset:64
	global_load_dwordx4 v[182:185], v[208:209], off offset:64
	global_load_dwordx4 v[138:141], v[166:167], off offset:512
	global_load_dwordx4 v[236:239], v[198:199], off offset:512
	global_load_dwordx4 v[186:189], v[208:209], off offset:512
	global_load_dwordx4 v[142:145], v[166:167], off offset:576
	global_load_dwordx4 v[240:243], v[198:199], off offset:576
	global_load_dwordx4 v[190:193], v[208:209], off offset:576
	v_and_b32_e32 v248, 15, v226
	v_lshrrev_b32_e32 v249, 8, v226
	v_lshl_or_b32 v248, v249, 6, v248
	v_lshl_add_u32 v248, v248, 2, s89
	ds_read_b32 v210, v248 offset:4096
	ds_read_b32 v212, v248 offset:4160
	ds_read_b32 v214, v248 offset:4224
	ds_read_b32 v216, v248 offset:4288
	ds_read_b32 v218, v248 offset:4608
	ds_read_b32 v220, v248 offset:4672
	ds_read_b32 v222, v248 offset:4736
	ds_read_b32 v224, v248 offset:4800
	v_lshlrev_b64 v[170:171], 1, v[158:159]
	v_lshlrev_b64 v[160:161], 11, v[176:177]
	v_lshl_add_u64 v[208:209], s[0:1], 0, v[160:161]
	v_lshl_add_u64 v[160:161], s[38:39], 0, v[160:161]
	v_lshl_add_u64 v[176:177], v[160:161], 0, v[170:171]
	v_lshl_add_u64 v[208:209], v[208:209], 0, v[170:171]
	v_bfe_u32 v156, v226, 4, 1
	v_mul_u32_u24_e32 v156, 24, v156
	v_mov_b32_e32 v157, 0
	v_lshl_add_u64 v[176:177], v[176:177], 0, v[156:157]
	v_lshl_add_u64 v[208:209], v[208:209], 0, v[156:157]
	s_mov_b32 s10, 0x8000
	s_mov_b32 s11, 0
	s_waitcnt vmcnt(0) lgkmcnt(0)
	v_pk_add_f32 v[228:229], v[228:229], 1.0 op_sel_hi:[1,0]
	v_pk_add_f32 v[230:231], v[230:231], 1.0 op_sel_hi:[1,0]
	v_pk_add_f32 v[232:233], v[232:233], 1.0 op_sel_hi:[1,0]
	v_pk_add_f32 v[234:235], v[234:235], 1.0 op_sel_hi:[1,0]
	v_pk_add_f32 v[236:237], v[236:237], 1.0 op_sel_hi:[1,0]
	v_pk_add_f32 v[238:239], v[238:239], 1.0 op_sel_hi:[1,0]
	v_pk_add_f32 v[240:241], v[240:241], 1.0 op_sel_hi:[1,0]
	v_pk_add_f32 v[242:243], v[242:243], 1.0 op_sel_hi:[1,0]
	v_cvt_pk_bf16_f32 v252, v164, v165
	v_cvt_pk_bf16_f32 v253, v162, v163
	v_cvt_pk_bf16_f32 v254, v126, v127
	v_cvt_pk_bf16_f32 v255, v122, v123
	s_nop 1
	v_permlane16_swap_b32_e32 v252, v254
	v_permlane16_swap_b32_e32 v253, v255
	global_store_dwordx4 v[208:209], v[252:255], off
	v_pk_mul_f32 v[164:165], v[164:165], v[210:211] op_sel_hi:[1,0]
	v_pk_mul_f32 v[162:163], v[162:163], v[210:211] op_sel_hi:[1,0]
	v_pk_mul_f32 v[164:165], v[130:131], v[164:165]
	v_pk_mul_f32 v[162:163], v[132:133], v[162:163]
	v_pk_fma_f32 v[164:165], v[228:229], v[164:165], v[178:179]
	v_pk_fma_f32 v[162:163], v[230:231], v[162:163], v[180:181]
	v_cvt_pk_bf16_f32 v148, v164, v165
	v_cvt_pk_bf16_f32 v149, v162, v163
	v_pk_mul_f32 v[126:127], v[126:127], v[210:211] op_sel_hi:[1,0]
	v_pk_mul_f32 v[122:123], v[122:123], v[210:211] op_sel_hi:[1,0]
	v_pk_mul_f32 v[126:127], v[134:135], v[126:127]
	v_pk_mul_f32 v[122:123], v[136:137], v[122:123]
	v_pk_fma_f32 v[126:127], v[232:233], v[126:127], v[182:183]
	v_pk_fma_f32 v[122:123], v[234:235], v[122:123], v[184:185]
	v_cvt_pk_bf16_f32 v150, v126, v127
	v_cvt_pk_bf16_f32 v151, v122, v123
	s_nop 1
	v_permlane16_swap_b32_e32 v148, v150
	v_permlane16_swap_b32_e32 v149, v151
	global_store_dwordx4 v[176:177], v[148:151], off
	v_cvt_pk_bf16_f32 v252, v116, v117
	v_cvt_pk_bf16_f32 v253, v118, v119
	v_cvt_pk_bf16_f32 v254, v112, v113
	v_cvt_pk_bf16_f32 v255, v114, v115
	s_nop 1
	v_permlane16_swap_b32_e32 v252, v254
	v_permlane16_swap_b32_e32 v253, v255
	global_store_dwordx4 v[208:209], v[252:255], off offset:256
	v_pk_mul_f32 v[116:117], v[116:117], v[210:211] op_sel_hi:[1,0]
	v_pk_mul_f32 v[118:119], v[118:119], v[210:211] op_sel_hi:[1,0]
	v_pk_mul_f32 v[116:117], v[138:139], v[116:117]
	v_pk_mul_f32 v[118:119], v[140:141], v[118:119]
	v_pk_fma_f32 v[116:117], v[236:237], v[116:117], v[186:187]
	v_pk_fma_f32 v[118:119], v[238:239], v[118:119], v[188:189]
	v_cvt_pk_bf16_f32 v152, v116, v117
	v_cvt_pk_bf16_f32 v153, v118, v119
	v_pk_mul_f32 v[112:113], v[112:113], v[210:211] op_sel_hi:[1,0]
	v_pk_mul_f32 v[114:115], v[114:115], v[210:211] op_sel_hi:[1,0]
	v_pk_mul_f32 v[112:113], v[142:143], v[112:113]
	v_pk_mul_f32 v[114:115], v[144:145], v[114:115]
	v_pk_fma_f32 v[112:113], v[240:241], v[112:113], v[190:191]
	v_pk_fma_f32 v[114:115], v[242:243], v[114:115], v[192:193]
	v_cvt_pk_bf16_f32 v154, v112, v113
	v_cvt_pk_bf16_f32 v155, v114, v115
	s_nop 1
	v_permlane16_swap_b32_e32 v152, v154
	v_permlane16_swap_b32_e32 v153, v155
	global_store_dwordx4 v[176:177], v[152:155], off offset:256
	v_lshl_add_u64 v[176:177], v[176:177], 0, s[10:11]
	v_lshl_add_u64 v[208:209], v[208:209], 0, s[10:11]
	v_cvt_pk_bf16_f32 v252, v108, v109
	v_cvt_pk_bf16_f32 v253, v110, v111
	v_cvt_pk_bf16_f32 v254, v104, v105
	v_cvt_pk_bf16_f32 v255, v106, v107
	s_nop 1
	v_permlane16_swap_b32_e32 v252, v254
	v_permlane16_swap_b32_e32 v253, v255
; DI unsigned pk2(float lo, float hi) { unsigned r; asm("v_cvt_pk_bf16_f32 %0, %1, %2" : "=v"(r) : "v"(lo), "v"(hi)); return r; }
;     DI void operator()(f32x4 (&acc)[2][2][4][2], const pg8::Unit& u, int wr, int wc, int fr, int fq) const {
;     ...
;                         u32x2 w; w.x = pk2(y.x, y.y); w.y = pk2(y.z, y.w); *(u32x2*)(xb + off) = w; }
;     ...
; #pragma unroll
;         for (int ai = 0; ai < 2; ++ai)
; #pragma unroll
;             for (int m = 0; m < 4; ++m) { const int rl = ai * 128 + wr * 64 + m * 16 + fr; const float rs = X[1024 + rl]; const size_t row = (size_t)u.pm * 256 + rl;
;                 const float* md = mod1 + (row >> 12) * 3072;
; #pragma unroll
;                 for (int bj = 0; bj < 2; ++bj)
; #pragma unroll
;                     for (int n = 0; n < 2; ++n) { const int col = col0 + bj * 128 + n * 16;
;                         const f32x4 gv = *(const f32x4*)(gno + col), sh = *(const f32x4*)(md + col), sc = *(const f32x4*)(md + 1024 + col);
;                         const f32x4 hv = acc[ai][bj][m][n] * rs * gv * (sc + 1.0f) + sh;
;                         u32x2 w; w.x = pk2(hv.x, hv.y); w.y = pk2(hv.z, hv.w); *(u32x2*)(H + row * DM + col) = w; }
	global_store_dwordx4 v[208:209], v[252:255], off
	v_pk_mul_f32 v[108:109], v[108:109], v[212:213] op_sel_hi:[1,0]
	v_pk_mul_f32 v[110:111], v[110:111], v[212:213] op_sel_hi:[1,0]
	v_pk_mul_f32 v[108:109], v[130:131], v[108:109]
	v_pk_mul_f32 v[110:111], v[132:133], v[110:111]
	v_pk_fma_f32 v[108:109], v[228:229], v[108:109], v[178:179]
	v_pk_fma_f32 v[110:111], v[230:231], v[110:111], v[180:181]
	v_cvt_pk_bf16_f32 v148, v108, v109
	v_cvt_pk_bf16_f32 v149, v110, v111
	v_pk_mul_f32 v[104:105], v[104:105], v[212:213] op_sel_hi:[1,0]
	v_pk_mul_f32 v[106:107], v[106:107], v[212:213] op_sel_hi:[1,0]
	v_pk_mul_f32 v[104:105], v[134:135], v[104:105]
	v_pk_mul_f32 v[106:107], v[136:137], v[106:107]
	v_pk_fma_f32 v[104:105], v[232:233], v[104:105], v[182:183]
	v_pk_fma_f32 v[106:107], v[234:235], v[106:107], v[184:185]
	v_cvt_pk_bf16_f32 v150, v104, v105
	v_cvt_pk_bf16_f32 v151, v106, v107
	s_nop 1
	v_permlane16_swap_b32_e32 v148, v150
	v_permlane16_swap_b32_e32 v149, v151
	global_store_dwordx4 v[176:177], v[148:151], off
	v_cvt_pk_bf16_f32 v252, v100, v101
	v_cvt_pk_bf16_f32 v253, v102, v103
	v_cvt_pk_bf16_f32 v254, v96, v97
	v_cvt_pk_bf16_f32 v255, v98, v99
	s_nop 1
	v_permlane16_swap_b32_e32 v252, v254
	v_permlane16_swap_b32_e32 v253, v255
	global_store_dwordx4 v[208:209], v[252:255], off offset:256
	v_pk_mul_f32 v[100:101], v[100:101], v[212:213] op_sel_hi:[1,0]
	v_pk_mul_f32 v[102:103], v[102:103], v[212:213] op_sel_hi:[1,0]
	v_pk_mul_f32 v[100:101], v[138:139], v[100:101]
	v_pk_mul_f32 v[102:103], v[140:141], v[102:103]
	v_pk_fma_f32 v[100:101], v[236:237], v[100:101], v[186:187]
	v_pk_fma_f32 v[102:103], v[238:239], v[102:103], v[188:189]
	v_cvt_pk_bf16_f32 v152, v100, v101
	v_cvt_pk_bf16_f32 v153, v102, v103
	v_pk_mul_f32 v[96:97], v[96:97], v[212:213] op_sel_hi:[1,0]
	v_pk_mul_f32 v[98:99], v[98:99], v[212:213] op_sel_hi:[1,0]
	v_pk_mul_f32 v[96:97], v[142:143], v[96:97]
	v_pk_mul_f32 v[98:99], v[144:145], v[98:99]
	v_pk_fma_f32 v[96:97], v[240:241], v[96:97], v[190:191]
	v_pk_fma_f32 v[98:99], v[242:243], v[98:99], v[192:193]
	v_cvt_pk_bf16_f32 v154, v96, v97
	v_cvt_pk_bf16_f32 v155, v98, v99
	s_nop 1
	v_permlane16_swap_b32_e32 v152, v154
	v_permlane16_swap_b32_e32 v153, v155
	global_store_dwordx4 v[176:177], v[152:155], off offset:256
	v_lshl_add_u64 v[176:177], v[176:177], 0, s[10:11]
	v_lshl_add_u64 v[208:209], v[208:209], 0, s[10:11]
	v_cvt_pk_bf16_f32 v252, v92, v93
	v_cvt_pk_bf16_f32 v253, v94, v95
	v_cvt_pk_bf16_f32 v254, v88, v89
	v_cvt_pk_bf16_f32 v255, v90, v91
	s_nop 1
	v_permlane16_swap_b32_e32 v252, v254
	v_permlane16_swap_b32_e32 v253, v255
	global_store_dwordx4 v[208:209], v[252:255], off
	v_pk_mul_f32 v[92:93], v[92:93], v[214:215] op_sel_hi:[1,0]
	v_pk_mul_f32 v[94:95], v[94:95], v[214:215] op_sel_hi:[1,0]
	v_pk_mul_f32 v[92:93], v[130:131], v[92:93]
	v_pk_mul_f32 v[94:95], v[132:133], v[94:95]
	v_pk_fma_f32 v[92:93], v[228:229], v[92:93], v[178:179]
	v_pk_fma_f32 v[94:95], v[230:231], v[94:95], v[180:181]
	v_cvt_pk_bf16_f32 v148, v92, v93
	v_cvt_pk_bf16_f32 v149, v94, v95
	v_pk_mul_f32 v[88:89], v[88:89], v[214:215] op_sel_hi:[1,0]
	v_pk_mul_f32 v[90:91], v[90:91], v[214:215] op_sel_hi:[1,0]
	v_pk_mul_f32 v[88:89], v[134:135], v[88:89]
	v_pk_mul_f32 v[90:91], v[136:137], v[90:91]
	v_pk_fma_f32 v[88:89], v[232:233], v[88:89], v[182:183]
	v_pk_fma_f32 v[90:91], v[234:235], v[90:91], v[184:185]
	v_cvt_pk_bf16_f32 v150, v88, v89
	v_cvt_pk_bf16_f32 v151, v90, v91
	s_nop 1
	v_permlane16_swap_b32_e32 v148, v150
	v_permlane16_swap_b32_e32 v149, v151
	global_store_dwordx4 v[176:177], v[148:151], off
	v_cvt_pk_bf16_f32 v252, v84, v85
	v_cvt_pk_bf16_f32 v253, v86, v87
	v_cvt_pk_bf16_f32 v254, v80, v81
	v_cvt_pk_bf16_f32 v255, v82, v83
	s_nop 1
	v_permlane16_swap_b32_e32 v252, v254
	v_permlane16_swap_b32_e32 v253, v255
	global_store_dwordx4 v[208:209], v[252:255], off offset:256
	v_pk_mul_f32 v[84:85], v[84:85], v[214:215] op_sel_hi:[1,0]
	v_pk_mul_f32 v[86:87], v[86:87], v[214:215] op_sel_hi:[1,0]
	v_pk_mul_f32 v[84:85], v[138:139], v[84:85]
	v_pk_mul_f32 v[86:87], v[140:141], v[86:87]
	v_pk_fma_f32 v[84:85], v[236:237], v[84:85], v[186:187]
	v_pk_fma_f32 v[86:87], v[238:239], v[86:87], v[188:189]
	v_cvt_pk_bf16_f32 v152, v84, v85
	v_cvt_pk_bf16_f32 v153, v86, v87
	v_pk_mul_f32 v[80:81], v[80:81], v[214:215] op_sel_hi:[1,0]
	v_pk_mul_f32 v[82:83], v[82:83], v[214:215] op_sel_hi:[1,0]
	v_pk_mul_f32 v[80:81], v[142:143], v[80:81]
	v_pk_mul_f32 v[82:83], v[144:145], v[82:83]
	v_pk_fma_f32 v[80:81], v[240:241], v[80:81], v[190:191]
	v_pk_fma_f32 v[82:83], v[242:243], v[82:83], v[192:193]
	v_cvt_pk_bf16_f32 v154, v80, v81
	v_cvt_pk_bf16_f32 v155, v82, v83
	s_nop 1
	v_permlane16_swap_b32_e32 v152, v154
	v_permlane16_swap_b32_e32 v153, v155
	global_store_dwordx4 v[176:177], v[152:155], off offset:256
	v_lshl_add_u64 v[176:177], v[176:177], 0, s[10:11]
	v_lshl_add_u64 v[208:209], v[208:209], 0, s[10:11]
	v_cvt_pk_bf16_f32 v252, v76, v77
	v_cvt_pk_bf16_f32 v253, v78, v79
	v_cvt_pk_bf16_f32 v254, v72, v73
	v_cvt_pk_bf16_f32 v255, v74, v75
	s_nop 1
	v_permlane16_swap_b32_e32 v252, v254
	v_permlane16_swap_b32_e32 v253, v255
	global_store_dwordx4 v[208:209], v[252:255], off
	v_pk_mul_f32 v[76:77], v[76:77], v[216:217] op_sel_hi:[1,0]
	v_pk_mul_f32 v[78:79], v[78:79], v[216:217] op_sel_hi:[1,0]
	v_pk_mul_f32 v[76:77], v[130:131], v[76:77]
	v_pk_mul_f32 v[78:79], v[132:133], v[78:79]
	v_pk_fma_f32 v[76:77], v[228:229], v[76:77], v[178:179]
	v_pk_fma_f32 v[78:79], v[230:231], v[78:79], v[180:181]
	v_cvt_pk_bf16_f32 v148, v76, v77
	v_cvt_pk_bf16_f32 v149, v78, v79
	v_pk_mul_f32 v[72:73], v[72:73], v[216:217] op_sel_hi:[1,0]
; DI unsigned pk2(float lo, float hi) { unsigned r; asm("v_cvt_pk_bf16_f32 %0, %1, %2" : "=v"(r) : "v"(lo), "v"(hi)); return r; }
;     DI void operator()(f32x4 (&acc)[2][2][4][2], const pg8::Unit& u, int wr, int wc, int fr, int fq) const {
;     ...
;                         u32x2 w; w.x = pk2(y.x, y.y); w.y = pk2(y.z, y.w); *(u32x2*)(xb + off) = w; }
;     ...
; #pragma unroll
;         for (int ai = 0; ai < 2; ++ai)
; #pragma unroll
;             for (int m = 0; m < 4; ++m) { const int rl = ai * 128 + wr * 64 + m * 16 + fr; const float rs = X[1024 + rl]; const size_t row = (size_t)u.pm * 256 + rl;
;                 const float* md = mod1 + (row >> 12) * 3072;
; #pragma unroll
;                 for (int bj = 0; bj < 2; ++bj)
; #pragma unroll
;                     for (int n = 0; n < 2; ++n) { const int col = col0 + bj * 128 + n * 16;
;                         const f32x4 gv = *(const f32x4*)(gno + col), sh = *(const f32x4*)(md + col), sc = *(const f32x4*)(md + 1024 + col);
;                         const f32x4 hv = acc[ai][bj][m][n] * rs * gv * (sc + 1.0f) + sh;
;                         u32x2 w; w.x = pk2(hv.x, hv.y); w.y = pk2(hv.z, hv.w); *(u32x2*)(H + row * DM + col) = w; }
	v_pk_mul_f32 v[74:75], v[74:75], v[216:217] op_sel_hi:[1,0]
	v_pk_mul_f32 v[72:73], v[134:135], v[72:73]
	v_pk_mul_f32 v[74:75], v[136:137], v[74:75]
	v_pk_fma_f32 v[72:73], v[232:233], v[72:73], v[182:183]
	v_pk_fma_f32 v[74:75], v[234:235], v[74:75], v[184:185]
	v_cvt_pk_bf16_f32 v150, v72, v73
	v_cvt_pk_bf16_f32 v151, v74, v75
	s_nop 1
	v_permlane16_swap_b32_e32 v148, v150
	v_permlane16_swap_b32_e32 v149, v151
	global_store_dwordx4 v[176:177], v[148:151], off
	v_cvt_pk_bf16_f32 v252, v68, v69
	v_cvt_pk_bf16_f32 v253, v70, v71
	v_cvt_pk_bf16_f32 v254, v64, v65
	v_cvt_pk_bf16_f32 v255, v66, v67
	s_nop 1
	v_permlane16_swap_b32_e32 v252, v254
	v_permlane16_swap_b32_e32 v253, v255
	global_store_dwordx4 v[208:209], v[252:255], off offset:256
	v_pk_mul_f32 v[68:69], v[68:69], v[216:217] op_sel_hi:[1,0]
	v_pk_mul_f32 v[70:71], v[70:71], v[216:217] op_sel_hi:[1,0]
	v_pk_mul_f32 v[68:69], v[138:139], v[68:69]
	v_pk_mul_f32 v[70:71], v[140:141], v[70:71]
	v_pk_fma_f32 v[68:69], v[236:237], v[68:69], v[186:187]
	v_pk_fma_f32 v[70:71], v[238:239], v[70:71], v[188:189]
	v_cvt_pk_bf16_f32 v152, v68, v69
	v_cvt_pk_bf16_f32 v153, v70, v71
	v_pk_mul_f32 v[64:65], v[64:65], v[216:217] op_sel_hi:[1,0]
	v_pk_mul_f32 v[66:67], v[66:67], v[216:217] op_sel_hi:[1,0]
	v_pk_mul_f32 v[64:65], v[142:143], v[64:65]
	v_pk_mul_f32 v[66:67], v[144:145], v[66:67]
	v_pk_fma_f32 v[64:65], v[240:241], v[64:65], v[190:191]
	v_pk_fma_f32 v[66:67], v[242:243], v[66:67], v[192:193]
	v_cvt_pk_bf16_f32 v154, v64, v65
	v_cvt_pk_bf16_f32 v155, v66, v67
	s_nop 1
	v_permlane16_swap_b32_e32 v152, v154
	v_permlane16_swap_b32_e32 v153, v155
	global_store_dwordx4 v[176:177], v[152:155], off offset:256
	s_mov_b32 s10, 0x28000
	v_lshl_add_u64 v[176:177], v[176:177], 0, s[10:11]
	v_lshl_add_u64 v[208:209], v[208:209], 0, s[10:11]
	s_mov_b32 s10, 0x8000
	v_cvt_pk_bf16_f32 v252, v60, v61
	v_cvt_pk_bf16_f32 v253, v62, v63
	v_cvt_pk_bf16_f32 v254, v56, v57
	v_cvt_pk_bf16_f32 v255, v58, v59
	s_nop 1
	v_permlane16_swap_b32_e32 v252, v254
	v_permlane16_swap_b32_e32 v253, v255
	global_store_dwordx4 v[208:209], v[252:255], off
	v_pk_mul_f32 v[60:61], v[60:61], v[218:219] op_sel_hi:[1,0]
	v_pk_mul_f32 v[62:63], v[62:63], v[218:219] op_sel_hi:[1,0]
	v_pk_mul_f32 v[60:61], v[130:131], v[60:61]
	v_pk_mul_f32 v[62:63], v[132:133], v[62:63]
	v_pk_fma_f32 v[60:61], v[228:229], v[60:61], v[178:179]
	v_pk_fma_f32 v[62:63], v[230:231], v[62:63], v[180:181]
	v_cvt_pk_bf16_f32 v148, v60, v61
	v_cvt_pk_bf16_f32 v149, v62, v63
	v_pk_mul_f32 v[56:57], v[56:57], v[218:219] op_sel_hi:[1,0]
	v_pk_mul_f32 v[58:59], v[58:59], v[218:219] op_sel_hi:[1,0]
	v_pk_mul_f32 v[56:57], v[134:135], v[56:57]
	v_pk_mul_f32 v[58:59], v[136:137], v[58:59]
	v_pk_fma_f32 v[56:57], v[232:233], v[56:57], v[182:183]
	v_pk_fma_f32 v[58:59], v[234:235], v[58:59], v[184:185]
	v_cvt_pk_bf16_f32 v150, v56, v57
	v_cvt_pk_bf16_f32 v151, v58, v59
	s_nop 1
	v_permlane16_swap_b32_e32 v148, v150
	v_permlane16_swap_b32_e32 v149, v151
	global_store_dwordx4 v[176:177], v[148:151], off
	v_cvt_pk_bf16_f32 v252, v52, v53
	v_cvt_pk_bf16_f32 v253, v54, v55
	v_cvt_pk_bf16_f32 v254, v48, v49
	v_cvt_pk_bf16_f32 v255, v50, v51
	s_nop 1
	v_permlane16_swap_b32_e32 v252, v254
	v_permlane16_swap_b32_e32 v253, v255
	global_store_dwordx4 v[208:209], v[252:255], off offset:256
	v_pk_mul_f32 v[52:53], v[52:53], v[218:219] op_sel_hi:[1,0]
	v_pk_mul_f32 v[54:55], v[54:55], v[218:219] op_sel_hi:[1,0]
	v_pk_mul_f32 v[52:53], v[138:139], v[52:53]
	v_pk_mul_f32 v[54:55], v[140:141], v[54:55]
	v_pk_fma_f32 v[52:53], v[236:237], v[52:53], v[186:187]
	v_pk_fma_f32 v[54:55], v[238:239], v[54:55], v[188:189]
	v_cvt_pk_bf16_f32 v152, v52, v53
	v_cvt_pk_bf16_f32 v153, v54, v55
	v_pk_mul_f32 v[48:49], v[48:49], v[218:219] op_sel_hi:[1,0]
	v_pk_mul_f32 v[50:51], v[50:51], v[218:219] op_sel_hi:[1,0]
	v_pk_mul_f32 v[48:49], v[142:143], v[48:49]
	v_pk_mul_f32 v[50:51], v[144:145], v[50:51]
	v_pk_fma_f32 v[48:49], v[240:241], v[48:49], v[190:191]
	v_pk_fma_f32 v[50:51], v[242:243], v[50:51], v[192:193]
	v_cvt_pk_bf16_f32 v154, v48, v49
	v_cvt_pk_bf16_f32 v155, v50, v51
	s_nop 1
	v_permlane16_swap_b32_e32 v152, v154
	v_permlane16_swap_b32_e32 v153, v155
	global_store_dwordx4 v[176:177], v[152:155], off offset:256
	v_lshl_add_u64 v[176:177], v[176:177], 0, s[10:11]
	v_lshl_add_u64 v[208:209], v[208:209], 0, s[10:11]
	v_cvt_pk_bf16_f32 v252, v44, v45
	v_cvt_pk_bf16_f32 v253, v46, v47
	v_cvt_pk_bf16_f32 v254, v40, v41
	v_cvt_pk_bf16_f32 v255, v42, v43
	s_nop 1
	v_permlane16_swap_b32_e32 v252, v254
	v_permlane16_swap_b32_e32 v253, v255
	global_store_dwordx4 v[208:209], v[252:255], off
	v_pk_mul_f32 v[44:45], v[44:45], v[220:221] op_sel_hi:[1,0]
	v_pk_mul_f32 v[46:47], v[46:47], v[220:221] op_sel_hi:[1,0]
	v_pk_mul_f32 v[44:45], v[130:131], v[44:45]
	v_pk_mul_f32 v[46:47], v[132:133], v[46:47]
	v_pk_fma_f32 v[44:45], v[228:229], v[44:45], v[178:179]
	v_pk_fma_f32 v[46:47], v[230:231], v[46:47], v[180:181]
	v_cvt_pk_bf16_f32 v148, v44, v45
	v_cvt_pk_bf16_f32 v149, v46, v47
	v_pk_mul_f32 v[40:41], v[40:41], v[220:221] op_sel_hi:[1,0]
	v_pk_mul_f32 v[42:43], v[42:43], v[220:221] op_sel_hi:[1,0]
	v_pk_mul_f32 v[40:41], v[134:135], v[40:41]
	v_pk_mul_f32 v[42:43], v[136:137], v[42:43]
	v_pk_fma_f32 v[40:41], v[232:233], v[40:41], v[182:183]
	v_pk_fma_f32 v[42:43], v[234:235], v[42:43], v[184:185]
	v_cvt_pk_bf16_f32 v150, v40, v41
	v_cvt_pk_bf16_f32 v151, v42, v43
	s_nop 1
	v_permlane16_swap_b32_e32 v148, v150
	v_permlane16_swap_b32_e32 v149, v151
	global_store_dwordx4 v[176:177], v[148:151], off
	v_cvt_pk_bf16_f32 v252, v36, v37
	v_cvt_pk_bf16_f32 v253, v38, v39
	v_cvt_pk_bf16_f32 v254, v32, v33
; DI unsigned pk2(float lo, float hi) { unsigned r; asm("v_cvt_pk_bf16_f32 %0, %1, %2" : "=v"(r) : "v"(lo), "v"(hi)); return r; }
;     DI void operator()(f32x4 (&acc)[2][2][4][2], const pg8::Unit& u, int wr, int wc, int fr, int fq) const {
;     ...
;                         u32x2 w; w.x = pk2(y.x, y.y); w.y = pk2(y.z, y.w); *(u32x2*)(xb + off) = w; }
;     ...
; #pragma unroll
;         for (int ai = 0; ai < 2; ++ai)
; #pragma unroll
;             for (int m = 0; m < 4; ++m) { const int rl = ai * 128 + wr * 64 + m * 16 + fr; const float rs = X[1024 + rl]; const size_t row = (size_t)u.pm * 256 + rl;
;                 const float* md = mod1 + (row >> 12) * 3072;
; #pragma unroll
;                 for (int bj = 0; bj < 2; ++bj)
; #pragma unroll
;                     for (int n = 0; n < 2; ++n) { const int col = col0 + bj * 128 + n * 16;
;                         const f32x4 gv = *(const f32x4*)(gno + col), sh = *(const f32x4*)(md + col), sc = *(const f32x4*)(md + 1024 + col);
;                         const f32x4 hv = acc[ai][bj][m][n] * rs * gv * (sc + 1.0f) + sh;
;                         u32x2 w; w.x = pk2(hv.x, hv.y); w.y = pk2(hv.z, hv.w); *(u32x2*)(H + row * DM + col) = w; }
;                 asm volatile("" ::: "memory"); }
;         asm volatile("s_waitcnt lgkmcnt(0)" ::: "memory"); __builtin_amdgcn_s_barrier(); asm volatile("" ::: "memory");
	v_cvt_pk_bf16_f32 v255, v34, v35
	s_nop 1
	v_permlane16_swap_b32_e32 v252, v254
	v_permlane16_swap_b32_e32 v253, v255
	global_store_dwordx4 v[208:209], v[252:255], off offset:256
	v_pk_mul_f32 v[36:37], v[36:37], v[220:221] op_sel_hi:[1,0]
	v_pk_mul_f32 v[38:39], v[38:39], v[220:221] op_sel_hi:[1,0]
	v_pk_mul_f32 v[36:37], v[138:139], v[36:37]
	v_pk_mul_f32 v[38:39], v[140:141], v[38:39]
	v_pk_fma_f32 v[36:37], v[236:237], v[36:37], v[186:187]
	v_pk_fma_f32 v[38:39], v[238:239], v[38:39], v[188:189]
	v_cvt_pk_bf16_f32 v152, v36, v37
	v_cvt_pk_bf16_f32 v153, v38, v39
	v_pk_mul_f32 v[32:33], v[32:33], v[220:221] op_sel_hi:[1,0]
	v_pk_mul_f32 v[34:35], v[34:35], v[220:221] op_sel_hi:[1,0]
	v_pk_mul_f32 v[32:33], v[142:143], v[32:33]
	v_pk_mul_f32 v[34:35], v[144:145], v[34:35]
	v_pk_fma_f32 v[32:33], v[240:241], v[32:33], v[190:191]
	v_pk_fma_f32 v[34:35], v[242:243], v[34:35], v[192:193]
	v_cvt_pk_bf16_f32 v154, v32, v33
	v_cvt_pk_bf16_f32 v155, v34, v35
	s_nop 1
	v_permlane16_swap_b32_e32 v152, v154
	v_permlane16_swap_b32_e32 v153, v155
	global_store_dwordx4 v[176:177], v[152:155], off offset:256
	v_lshl_add_u64 v[176:177], v[176:177], 0, s[10:11]
	v_lshl_add_u64 v[208:209], v[208:209], 0, s[10:11]
	v_cvt_pk_bf16_f32 v252, v28, v29
	v_cvt_pk_bf16_f32 v253, v30, v31
	v_cvt_pk_bf16_f32 v254, v24, v25
	v_cvt_pk_bf16_f32 v255, v26, v27
	s_nop 1
	v_permlane16_swap_b32_e32 v252, v254
	v_permlane16_swap_b32_e32 v253, v255
	global_store_dwordx4 v[208:209], v[252:255], off
	v_pk_mul_f32 v[28:29], v[28:29], v[222:223] op_sel_hi:[1,0]
	v_pk_mul_f32 v[30:31], v[30:31], v[222:223] op_sel_hi:[1,0]
	v_pk_mul_f32 v[28:29], v[130:131], v[28:29]
	v_pk_mul_f32 v[30:31], v[132:133], v[30:31]
	v_pk_fma_f32 v[28:29], v[228:229], v[28:29], v[178:179]
	v_pk_fma_f32 v[30:31], v[230:231], v[30:31], v[180:181]
	v_cvt_pk_bf16_f32 v148, v28, v29
	v_cvt_pk_bf16_f32 v149, v30, v31
	v_pk_mul_f32 v[24:25], v[24:25], v[222:223] op_sel_hi:[1,0]
	v_pk_mul_f32 v[26:27], v[26:27], v[222:223] op_sel_hi:[1,0]
	v_pk_mul_f32 v[24:25], v[134:135], v[24:25]
	v_pk_mul_f32 v[26:27], v[136:137], v[26:27]
	v_pk_fma_f32 v[24:25], v[232:233], v[24:25], v[182:183]
	v_pk_fma_f32 v[26:27], v[234:235], v[26:27], v[184:185]
	v_cvt_pk_bf16_f32 v150, v24, v25
	v_cvt_pk_bf16_f32 v151, v26, v27
	s_nop 1
	v_permlane16_swap_b32_e32 v148, v150
	v_permlane16_swap_b32_e32 v149, v151
	global_store_dwordx4 v[176:177], v[148:151], off
	v_cvt_pk_bf16_f32 v252, v20, v21
	v_cvt_pk_bf16_f32 v253, v22, v23
	v_cvt_pk_bf16_f32 v254, v16, v17
	v_cvt_pk_bf16_f32 v255, v18, v19
	s_nop 1
	v_permlane16_swap_b32_e32 v252, v254
	v_permlane16_swap_b32_e32 v253, v255
	global_store_dwordx4 v[208:209], v[252:255], off offset:256
	v_pk_mul_f32 v[20:21], v[20:21], v[222:223] op_sel_hi:[1,0]
	v_pk_mul_f32 v[22:23], v[22:23], v[222:223] op_sel_hi:[1,0]
	v_pk_mul_f32 v[20:21], v[138:139], v[20:21]
	v_pk_mul_f32 v[22:23], v[140:141], v[22:23]
	v_pk_fma_f32 v[20:21], v[236:237], v[20:21], v[186:187]
	v_pk_fma_f32 v[22:23], v[238:239], v[22:23], v[188:189]
	v_cvt_pk_bf16_f32 v152, v20, v21
	v_cvt_pk_bf16_f32 v153, v22, v23
	v_pk_mul_f32 v[16:17], v[16:17], v[222:223] op_sel_hi:[1,0]
	v_pk_mul_f32 v[18:19], v[18:19], v[222:223] op_sel_hi:[1,0]
	v_pk_mul_f32 v[16:17], v[142:143], v[16:17]
	v_pk_mul_f32 v[18:19], v[144:145], v[18:19]
	v_pk_fma_f32 v[16:17], v[240:241], v[16:17], v[190:191]
	v_pk_fma_f32 v[18:19], v[242:243], v[18:19], v[192:193]
	v_cvt_pk_bf16_f32 v154, v16, v17
	v_cvt_pk_bf16_f32 v155, v18, v19
	s_nop 1
	v_permlane16_swap_b32_e32 v152, v154
	v_permlane16_swap_b32_e32 v153, v155
	global_store_dwordx4 v[176:177], v[152:155], off offset:256
	v_lshl_add_u64 v[176:177], v[176:177], 0, s[10:11]
	v_lshl_add_u64 v[208:209], v[208:209], 0, s[10:11]
	v_cvt_pk_bf16_f32 v252, v12, v13
	v_cvt_pk_bf16_f32 v253, v14, v15
	v_cvt_pk_bf16_f32 v254, v8, v9
	v_cvt_pk_bf16_f32 v255, v10, v11
	s_nop 1
	v_permlane16_swap_b32_e32 v252, v254
	v_permlane16_swap_b32_e32 v253, v255
	global_store_dwordx4 v[208:209], v[252:255], off
	v_pk_mul_f32 v[12:13], v[12:13], v[224:225] op_sel_hi:[1,0]
	v_pk_mul_f32 v[14:15], v[14:15], v[224:225] op_sel_hi:[1,0]
	v_pk_mul_f32 v[12:13], v[130:131], v[12:13]
	v_pk_mul_f32 v[14:15], v[132:133], v[14:15]
	v_pk_fma_f32 v[12:13], v[228:229], v[12:13], v[178:179]
	v_pk_fma_f32 v[14:15], v[230:231], v[14:15], v[180:181]
	v_cvt_pk_bf16_f32 v148, v12, v13
	v_cvt_pk_bf16_f32 v149, v14, v15
	v_pk_mul_f32 v[8:9], v[8:9], v[224:225] op_sel_hi:[1,0]
	v_pk_mul_f32 v[10:11], v[10:11], v[224:225] op_sel_hi:[1,0]
	v_pk_mul_f32 v[8:9], v[134:135], v[8:9]
	v_pk_mul_f32 v[10:11], v[136:137], v[10:11]
	v_pk_fma_f32 v[8:9], v[232:233], v[8:9], v[182:183]
	v_pk_fma_f32 v[10:11], v[234:235], v[10:11], v[184:185]
	v_cvt_pk_bf16_f32 v150, v8, v9
	v_cvt_pk_bf16_f32 v151, v10, v11
	s_nop 1
	v_permlane16_swap_b32_e32 v148, v150
	v_permlane16_swap_b32_e32 v149, v151
	global_store_dwordx4 v[176:177], v[148:151], off
	v_cvt_pk_bf16_f32 v252, v4, v5
	v_cvt_pk_bf16_f32 v253, v6, v7
	v_cvt_pk_bf16_f32 v254, v0, v1
	v_cvt_pk_bf16_f32 v255, v2, v3
	s_nop 1
	v_permlane16_swap_b32_e32 v252, v254
	v_permlane16_swap_b32_e32 v253, v255
	global_store_dwordx4 v[208:209], v[252:255], off offset:256
	v_pk_mul_f32 v[4:5], v[4:5], v[224:225] op_sel_hi:[1,0]
	v_pk_mul_f32 v[6:7], v[6:7], v[224:225] op_sel_hi:[1,0]
	v_pk_mul_f32 v[4:5], v[138:139], v[4:5]
	v_pk_mul_f32 v[6:7], v[140:141], v[6:7]
	v_pk_fma_f32 v[4:5], v[236:237], v[4:5], v[186:187]
	v_pk_fma_f32 v[6:7], v[238:239], v[6:7], v[188:189]
	v_cvt_pk_bf16_f32 v152, v4, v5
	v_cvt_pk_bf16_f32 v153, v6, v7
	v_pk_mul_f32 v[0:1], v[0:1], v[224:225] op_sel_hi:[1,0]
	v_pk_mul_f32 v[2:3], v[2:3], v[224:225] op_sel_hi:[1,0]
	v_pk_mul_f32 v[0:1], v[142:143], v[0:1]
	v_pk_mul_f32 v[2:3], v[144:145], v[2:3]
	v_pk_fma_f32 v[0:1], v[240:241], v[0:1], v[190:191]
	v_pk_fma_f32 v[2:3], v[242:243], v[2:3], v[192:193]
	v_cvt_pk_bf16_f32 v154, v0, v1
	v_cvt_pk_bf16_f32 v155, v2, v3
	s_nop 1
	v_permlane16_swap_b32_e32 v152, v154
	v_permlane16_swap_b32_e32 v153, v155
	global_store_dwordx4 v[176:177], v[152:155], off offset:256
	s_andn2_b64 vcc, exec, s[8:9]
	s_mov_b64 s[8:9], -1
	s_waitcnt lgkmcnt(0)
	s_barrier
	s_cbranch_vccnz .LBB0_765
	s_andn2_b64 vcc, exec, s[16:17]
	s_cbranch_vccnz .LBB0_764
	s_barrier
	s_branch .LBB0_764
